# grid-barrier poll loops sleep 4 instead of 16 between counter reads (lower exit latency at each of the 11 grid syncs)
# baseline (speedup 1.0000x reference)
.LBB0_86:
	s_sleep 4
	global_load_dword v1, v0, s[78:79] sc1
	s_waitcnt vmcnt(0)
	v_cmp_gt_u32_e32 vcc, s50, v1
	s_cbranch_vccnz .LBB0_86

.LBB0_1071:
	s_sleep 4
	global_load_dword v1, v0, s[78:79] sc1
	s_waitcnt vmcnt(0)
	v_cmp_gt_u32_e32 vcc, s3, v1
	s_cbranch_vccnz .LBB0_1071

.LBB0_1211:
	s_sleep 4
	global_load_dword v1, v0, s[36:37] sc1
	s_waitcnt vmcnt(0)
	v_cmp_gt_u32_e32 vcc, s3, v1
	s_cbranch_vccnz .LBB0_1211
